# combined stack + phase-4 Toeplitz expansion fast path (all eight predicated load pairs issued before the stores at 256 workgroups)
# baseline (speedup 1.0000x reference)
.LBB0_90:
	s_and_b64 vcc, exec, s[6:7]
	s_cbranch_vccz .LBB0_129
	s_mov_b64 s[14:15], 0
	v_writelane_b32 v255, s14, 33
	s_mov_b64 s[6:7], -1
	s_cmp_gt_i32 s35, 1
	v_writelane_b32 v255, s15, 34
	s_cbranch_scc0 .LBB0_136
	s_mov_b64 s[6:7], 0
	s_cmp_gt_i32 s35, 2
	s_cbranch_scc0 .LBB0_137
	s_cmp_gt_i32 s35, 3
	s_mov_b64 s[22:23], -1
	s_cbranch_scc0 .LBB0_141
	s_cmp_eq_u32 s35, 4
	s_cbranch_scc0 .LBB0_140
	v_readlane_b32 s10, v252, 30
	v_readlane_b32 s11, v252, 31
	s_andn2_b64 vcc, exec, s[10:11]
	s_cbranch_vccnz .LBB0_139
	v_lshlrev_b32_e32 v0, 5, v138
	v_readlane_b32 s10, v252, 32
	v_and_b32_e32 v0, 32, v0
	s_waitcnt lgkmcnt(0)
	v_mov_b32_e32 v1, v81
	v_readlane_b32 s11, v252, 33
	v_and_b32_e32 v2, 63, v138
	v_readlane_b32 s4, v254, 58
	v_lshl_add_u64 v[4:5], s[10:11], 0, v[0:1]
	v_readlane_b32 s10, v252, 34
	v_lshlrev_b32_e32 v0, 4, v2
	v_readlane_b32 s11, v252, 35
	v_bfe_u32 v12, v138, 1, 5
	v_add_u32_e32 v13, s4, v138
	v_lshl_add_u64 v[6:7], s[10:11], 0, v[0:1]
	s_mov_b32 s4, s2
	s_cmp_eq_u32 s3, 0x100
	s_cbranch_scc0 .LBB0_132
	v_lshrrev_b32_e32 v0, 6, v13
	v_bfe_u32 v0, v0, 4, 5
	v_ashrrev_i32_e32 v10, 15, v13
	v_cmp_ge_u32_e64 s[14:15], v0, v12
	v_sub_u32_e32 v0, v0, v12
	v_bfe_u32 v1, v13, 6, 4
	v_lshlrev_b32_e32 v0, 4, v0
	v_lshlrev_b32_e32 v8, 9, v10
	v_or3_b32 v0, v0, v1, v8
	v_lshlrev_b32_e32 v0, 6, v0
	v_mov_b32_e32 v1, v81
	v_lshl_add_u64 v[14:15], v[4:5], 0, v[0:1]
	v_bfe_u32 v9, v13, 6, 9
	v_or_b32_e32 v8, v8, v9
	v_mul_u32_u24_e32 v8, 0x500, v8
	v_mov_b32_e32 v9, v81
	v_lshl_add_u64 v[16:17], v[6:7], 0, v[8:9]
	s_and_saveexec_b64 s[10:11], s[14:15]
	s_cbranch_execz .Ltoep_nold
	global_load_dwordx4 v[20:23], v[14:15], off
	global_load_dwordx4 v[24:27], v[14:15], off offset:16
	s_mov_b64 vcc, 0x20000
	s_nop 0
	v_lshl_add_u64 v[14:15], v[14:15], 0, vcc
	global_load_dwordx4 v[28:31], v[14:15], off
	global_load_dwordx4 v[32:35], v[14:15], off offset:16
	s_mov_b64 vcc, 0x20000
	s_nop 0
	v_lshl_add_u64 v[14:15], v[14:15], 0, vcc
	global_load_dwordx4 v[36:39], v[14:15], off
	global_load_dwordx4 v[40:43], v[14:15], off offset:16
	s_mov_b64 vcc, 0x20000
	s_nop 0
	v_lshl_add_u64 v[14:15], v[14:15], 0, vcc
	global_load_dwordx4 v[44:47], v[14:15], off
	global_load_dwordx4 v[48:51], v[14:15], off offset:16
	s_mov_b64 vcc, 0x20000
	s_nop 0
	v_lshl_add_u64 v[14:15], v[14:15], 0, vcc
	global_load_dwordx4 v[52:55], v[14:15], off
	global_load_dwordx4 v[56:59], v[14:15], off offset:16
	s_mov_b64 vcc, 0x20000
	s_nop 0
	v_lshl_add_u64 v[14:15], v[14:15], 0, vcc
	global_load_dwordx4 v[60:63], v[14:15], off
	global_load_dwordx4 v[64:67], v[14:15], off offset:16
	s_mov_b64 vcc, 0x20000
	s_nop 0
	v_lshl_add_u64 v[14:15], v[14:15], 0, vcc
	global_load_dwordx4 v[68:71], v[14:15], off
	global_load_dwordx4 v[72:75], v[14:15], off offset:16
	s_mov_b64 vcc, 0x20000
	s_nop 0
	v_lshl_add_u64 v[14:15], v[14:15], 0, vcc
	global_load_dwordx4 v[84:87], v[14:15], off
	global_load_dwordx4 v[88:91], v[14:15], off offset:16
.Ltoep_nold:
	s_or_b64 exec, exec, s[10:11]
	s_waitcnt vmcnt(14)
	v_cvt_pk_bf16_f32 v20, v20, v21
	v_cvt_pk_bf16_f32 v21, v22, v23
	v_cvt_pk_bf16_f32 v22, v24, v25
	v_cvt_pk_bf16_f32 v23, v26, v27
	v_cndmask_b32_e64 v20, 0, v20, s[14:15]
	v_cndmask_b32_e64 v21, 0, v21, s[14:15]
	v_cndmask_b32_e64 v22, 0, v22, s[14:15]
	v_cndmask_b32_e64 v23, 0, v23, s[14:15]
	global_store_dwordx4 v[16:17], v[20:23], off
	s_mov_b64 vcc, 0x280000
	s_nop 0
	v_lshl_add_u64 v[16:17], v[16:17], 0, vcc
	s_waitcnt vmcnt(13)
	v_cvt_pk_bf16_f32 v28, v28, v29
	v_cvt_pk_bf16_f32 v29, v30, v31
	v_cvt_pk_bf16_f32 v30, v32, v33
	v_cvt_pk_bf16_f32 v31, v34, v35
	v_cndmask_b32_e64 v28, 0, v28, s[14:15]
	v_cndmask_b32_e64 v29, 0, v29, s[14:15]
	v_cndmask_b32_e64 v30, 0, v30, s[14:15]
	v_cndmask_b32_e64 v31, 0, v31, s[14:15]
	global_store_dwordx4 v[16:17], v[28:31], off
	s_mov_b64 vcc, 0x280000
	s_nop 0
	v_lshl_add_u64 v[16:17], v[16:17], 0, vcc
	s_waitcnt vmcnt(12)
	v_cvt_pk_bf16_f32 v36, v36, v37
	v_cvt_pk_bf16_f32 v37, v38, v39
	v_cvt_pk_bf16_f32 v38, v40, v41
	v_cvt_pk_bf16_f32 v39, v42, v43
	v_cndmask_b32_e64 v36, 0, v36, s[14:15]
	v_cndmask_b32_e64 v37, 0, v37, s[14:15]
	v_cndmask_b32_e64 v38, 0, v38, s[14:15]
	v_cndmask_b32_e64 v39, 0, v39, s[14:15]
	global_store_dwordx4 v[16:17], v[36:39], off
	s_mov_b64 vcc, 0x280000
	s_nop 0
	v_lshl_add_u64 v[16:17], v[16:17], 0, vcc
	s_waitcnt vmcnt(11)
	v_cvt_pk_bf16_f32 v44, v44, v45
	v_cvt_pk_bf16_f32 v45, v46, v47
	v_cvt_pk_bf16_f32 v46, v48, v49
	v_cvt_pk_bf16_f32 v47, v50, v51
	v_cndmask_b32_e64 v44, 0, v44, s[14:15]
	v_cndmask_b32_e64 v45, 0, v45, s[14:15]
	v_cndmask_b32_e64 v46, 0, v46, s[14:15]
	v_cndmask_b32_e64 v47, 0, v47, s[14:15]
	global_store_dwordx4 v[16:17], v[44:47], off
	s_mov_b64 vcc, 0x280000
	s_nop 0
	v_lshl_add_u64 v[16:17], v[16:17], 0, vcc
	s_waitcnt vmcnt(10)
	v_cvt_pk_bf16_f32 v52, v52, v53
	v_cvt_pk_bf16_f32 v53, v54, v55
	v_cvt_pk_bf16_f32 v54, v56, v57
	v_cvt_pk_bf16_f32 v55, v58, v59
	v_cndmask_b32_e64 v52, 0, v52, s[14:15]
	v_cndmask_b32_e64 v53, 0, v53, s[14:15]
	v_cndmask_b32_e64 v54, 0, v54, s[14:15]
	v_cndmask_b32_e64 v55, 0, v55, s[14:15]
	global_store_dwordx4 v[16:17], v[52:55], off
	s_mov_b64 vcc, 0x280000
	s_nop 0
	v_lshl_add_u64 v[16:17], v[16:17], 0, vcc
	s_waitcnt vmcnt(9)
	v_cvt_pk_bf16_f32 v60, v60, v61
	v_cvt_pk_bf16_f32 v61, v62, v63
	v_cvt_pk_bf16_f32 v62, v64, v65
	v_cvt_pk_bf16_f32 v63, v66, v67
	v_cndmask_b32_e64 v60, 0, v60, s[14:15]
	v_cndmask_b32_e64 v61, 0, v61, s[14:15]
	v_cndmask_b32_e64 v62, 0, v62, s[14:15]
	v_cndmask_b32_e64 v63, 0, v63, s[14:15]
	global_store_dwordx4 v[16:17], v[60:63], off
	s_mov_b64 vcc, 0x280000
	s_nop 0
	v_lshl_add_u64 v[16:17], v[16:17], 0, vcc
	s_waitcnt vmcnt(8)
	v_cvt_pk_bf16_f32 v68, v68, v69
	v_cvt_pk_bf16_f32 v69, v70, v71
	v_cvt_pk_bf16_f32 v70, v72, v73
	v_cvt_pk_bf16_f32 v71, v74, v75
	v_cndmask_b32_e64 v68, 0, v68, s[14:15]
	v_cndmask_b32_e64 v69, 0, v69, s[14:15]
	v_cndmask_b32_e64 v70, 0, v70, s[14:15]
	v_cndmask_b32_e64 v71, 0, v71, s[14:15]
	global_store_dwordx4 v[16:17], v[68:71], off
	s_mov_b64 vcc, 0x280000
	s_nop 0
	v_lshl_add_u64 v[16:17], v[16:17], 0, vcc
	s_waitcnt vmcnt(7)
	v_cvt_pk_bf16_f32 v84, v84, v85
	v_cvt_pk_bf16_f32 v85, v86, v87
	v_cvt_pk_bf16_f32 v86, v88, v89
	v_cvt_pk_bf16_f32 v87, v90, v91
	v_cndmask_b32_e64 v84, 0, v84, s[14:15]
	v_cndmask_b32_e64 v85, 0, v85, s[14:15]
	v_cndmask_b32_e64 v86, 0, v86, s[14:15]
	v_cndmask_b32_e64 v87, 0, v87, s[14:15]
	global_store_dwordx4 v[16:17], v[84:87], off
	s_branch .LBB0_139
	s_branch .LBB0_132
